# EpiUp (MLP-up GEMM) epilogue: the 8 per-row SSQ loads hoisted to the epilogue start with counted vmcnt waits (was load -> vmcnt(0) -> 2 stores, 8 times per unit)
# baseline (speedup 1.0000x reference)
; __device__ __forceinline__ void st_bf8(bf16* p, f32x4 a, f32x4 b) { u32x4 w; w.x = pk2(a[0], a[1]); w.y = pk2(a[2], a[3]); w.z = pk2(b[0], b[1]); w.w = pk2(b[2], b[3]); *(u32x4*)p = w; }
;     __device__ __forceinline__ void operator()(AccRef acc, const pg8::Unit& u, int wr, int wc, int fr, int fq) const {
;         const int c0 = u.pn * 256;
; #pragma unroll
;         for (int ai = 0; ai < 2; ++ai)
; #pragma unroll
;             for (int m = 0; m < 4; ++m) {
;                 const int row = u.pm * 256 + ai * 128 + wr * 64 + m * 16 + fr; const size_t rw = (size_t)row;
;                 const float rs2 = 1.0f / (SSQ[row] * (1.f / 1024.f) + EPSN);
; #pragma unroll
;                 for (int bj = 0; bj < 2; ++bj) {
;                     const int cl = bj * 128 + wc * 32 + 8 * fq; const f32x4 v0 = acc[ai][bj][m][0], v1 = acc[ai][bj][m][1];
;                     f32x4 r0, r1; r0[0] = fmaxf(v0[0], 0.f); r0[1] = fmaxf(v0[1], 0.f); r0[2] = fmaxf(v0[2], 0.f); r0[3] = fmaxf(v0[3], 0.f); r1[0] = fmaxf(v1[0], 0.f); r1[1] = fmaxf(v1[1], 0.f); r1[2] = fmaxf(v1[2], 0.f); r1[3] = fmaxf(v1[3], 0.f);
;                     st_bf8(U + rw * 4096 + c0 + cl, r0 * r0 * rs2, r1 * r1 * rs2);
;                 }
;                 asm volatile("" ::: "memory");
;             }
;     }
.LBB0_333:
	v_lshl_add_u32 v140, s57, 8, v145
	v_ashrrev_i32_e32 v141, 31, v140
	v_lshl_add_u64 v[142:143], v[140:141], 2, s[18:19]
	global_load_dword v160, v[142:143], off
	global_load_dword v161, v[142:143], off offset:64
	global_load_dword v162, v[142:143], off offset:128
	global_load_dword v163, v[142:143], off offset:192
	global_load_dword v164, v[142:143], off offset:512
	global_load_dword v165, v[142:143], off offset:576
	global_load_dword v166, v[142:143], off offset:640
	global_load_dword v167, v[142:143], off offset:704
	v_max_f32_e32 v120, v120, v120
	v_max_f32_e32 v121, v121, v121
	v_max_f32_e32 v148, v116, v116
	v_max_f32_e32 v149, v117, v117
	v_max_f32_e32 v116, 0, v120
	v_max_f32_e32 v117, 0, v121
	v_max_f32_e32 v120, 0, v148
	v_max_f32_e32 v121, 0, v149
	v_lshlrev_b64 v[148:149], 13, v[140:141]
	v_max_f32_e32 v122, v122, v122
	v_max_f32_e32 v151, v118, v118
	v_max_f32_e32 v118, 0, v122
	v_max_f32_e32 v122, 0, v151
	v_max_f32_e32 v124, v124, v124
	v_max_f32_e32 v153, v112, v112
	v_max_f32_e32 v123, v123, v123
	v_max_f32_e32 v152, v119, v119
	v_max_f32_e32 v112, 0, v124
	v_max_f32_e32 v124, 0, v153
	v_max_f32_e32 v119, 0, v123
	v_max_f32_e32 v123, 0, v152
	v_max_f32_e32 v125, v125, v125
	v_max_f32_e32 v154, v113, v113
	v_max_f32_e32 v113, 0, v125
	v_max_f32_e32 v125, 0, v154
	s_lshl_b32 s26, s58, 8
	v_max_f32_e32 v126, v126, v126
	v_max_f32_e32 v127, v127, v127
	v_max_f32_e32 v155, v114, v114
	v_max_f32_e32 v156, v115, v115
	s_ashr_i32 s27, s26, 31
	v_max_f32_e32 v114, 0, v126
	v_max_f32_e32 v115, 0, v127
	v_max_f32_e32 v126, 0, v155
	v_max_f32_e32 v127, 0, v156
	s_lshl_b64 s[26:27], s[26:27], 1
	v_pk_mul_f32 v[112:113], v[112:113], v[112:113]
	v_pk_mul_f32 v[114:115], v[114:115], v[114:115]
	v_pk_mul_f32 v[116:117], v[116:117], v[116:117]
	v_pk_mul_f32 v[118:119], v[118:119], v[118:119]
	v_lshl_add_u64 v[148:149], s[10:11], 0, v[148:149]
	v_pk_mul_f32 v[120:121], v[120:121], v[120:121]
	v_pk_mul_f32 v[122:123], v[122:123], v[122:123]
	v_pk_mul_f32 v[124:125], v[124:125], v[124:125]
	v_pk_mul_f32 v[126:127], v[126:127], v[126:127]
	v_lshl_add_u64 v[148:149], v[148:149], 0, s[26:27]
	v_lshl_add_u64 v[148:149], v[148:149], 0, v[184:185]
	v_max_f32_e32 v109, v109, v109
	v_max_f32_e32 v110, v110, v110
	v_max_f32_e32 v111, v111, v111
	v_max_f32_e32 v104, v104, v104
	v_max_f32_e32 v106, v106, v106
	v_max_f32_e32 v97, v97, v97
	v_max_f32_e32 v108, v108, v108
	v_max_f32_e32 v105, v105, v105
	v_max_f32_e32 v107, v107, v107
	v_max_f32_e32 v93, v93, v93
	v_max_f32_e32 v94, v94, v94
	v_max_f32_e32 v95, v95, v95
	v_max_f32_e32 v88, v88, v88
	v_max_f32_e32 v90, v90, v90
	v_max_f32_e32 v81, v81, v81
	v_max_f32_e32 v92, v92, v92
	v_max_f32_e32 v89, v89, v89
	v_max_f32_e32 v91, v91, v91
	v_max_f32_e32 v77, v77, v77
	v_max_f32_e32 v78, v78, v78
	v_max_f32_e32 v79, v79, v79
	v_max_f32_e32 v72, v72, v72
	v_max_f32_e32 v74, v74, v74
	v_max_f32_e32 v65, v65, v65
	v_max_f32_e32 v76, v76, v76
	v_max_f32_e32 v73, v73, v73
	v_max_f32_e32 v75, v75, v75
	v_max_f32_e32 v61, v61, v61
	v_max_f32_e32 v62, v62, v62
	v_max_f32_e32 v63, v63, v63
	v_max_f32_e32 v56, v56, v56
	v_max_f32_e32 v58, v58, v58
	s_waitcnt vmcnt(7)
	v_fmamk_f32 v141, v160, 0x3a800000, v205
	v_div_scale_f32 v150, s[28:29], v141, v141, 1.0
	v_rcp_f32_e32 v151, v150
	v_div_scale_f32 v152, vcc, 1.0, v141, 1.0
	v_max_f32_e32 v49, v49, v49
	v_fma_f32 v153, -v150, v151, 1.0
	v_fmac_f32_e32 v151, v153, v151
	v_mul_f32_e32 v153, v152, v151
	v_fma_f32 v154, -v150, v153, v152
	v_fmac_f32_e32 v153, v154, v151
	v_fma_f32 v150, -v150, v153, v152
	v_div_fmas_f32 v150, v150, v151, v153
	v_div_fixup_f32 v150, v150, v141, 1.0
	v_pk_mul_f32 v[114:115], v[114:115], v[150:151] op_sel_hi:[1,0]
	v_pk_mul_f32 v[112:113], v[112:113], v[150:151] op_sel_hi:[1,0]
	v_pk_mul_f32 v[118:119], v[118:119], v[150:151] op_sel_hi:[1,0]
	v_pk_mul_f32 v[116:117], v[116:117], v[150:151] op_sel_hi:[1,0]
	v_pk_mul_f32 v[122:123], v[122:123], v[150:151] op_sel_hi:[1,0]
	v_pk_mul_f32 v[120:121], v[120:121], v[150:151] op_sel_hi:[1,0]
	v_pk_mul_f32 v[126:127], v[126:127], v[150:151] op_sel_hi:[1,0]
	v_pk_mul_f32 v[124:125], v[124:125], v[150:151] op_sel_hi:[1,0]
	v_cvt_pk_bf16_f32 v112, v112, v113
	v_cvt_pk_bf16_f32 v113, v114, v115
	v_cvt_pk_bf16_f32 v114, v116, v117
	v_cvt_pk_bf16_f32 v115, v118, v119
	v_cvt_pk_bf16_f32 v116, v120, v121
	v_cvt_pk_bf16_f32 v117, v122, v123
	v_cvt_pk_bf16_f32 v118, v124, v125
	v_cvt_pk_bf16_f32 v119, v126, v127
	global_store_dwordx4 v[148:149], v[112:115], off
	global_store_dwordx4 v[148:149], v[116:119], off offset:256
	s_nop 1
	v_max_f32_e32 v112, v100, v100
	v_max_f32_e32 v116, v103, v103
	v_max_f32_e32 v117, v96, v96
	v_max_f32_e32 v119, v99, v99
	v_max_f32_e32 v99, 0, v109
	v_max_f32_e32 v109, 0, v116
	v_max_f32_e32 v118, v98, v98
	v_or_b32_e32 v96, 16, v140
	v_max_f32_e32 v100, 0, v110
	v_max_f32_e32 v110, 0, v117
	v_max_f32_e32 v113, v101, v101
	v_max_f32_e32 v115, v102, v102
	v_max_f32_e32 v101, 0, v111
	v_max_f32_e32 v102, 0, v104
	v_max_f32_e32 v104, 0, v106
	v_max_f32_e32 v106, 0, v112
	v_max_f32_e32 v111, 0, v97
	v_max_f32_e32 v112, 0, v118
	v_ashrrev_i32_e32 v97, 31, v96
	v_lshlrev_b64 v[96:97], 13, v[96:97]
	v_lshl_add_u64 v[96:97], s[10:11], 0, v[96:97]
	v_lshl_add_u64 v[96:97], v[96:97], 0, s[26:27]
	v_max_f32_e32 v98, 0, v108
	v_max_f32_e32 v108, 0, v115
	v_max_f32_e32 v103, 0, v105
	v_max_f32_e32 v105, 0, v107
	v_max_f32_e32 v107, 0, v113
	v_max_f32_e32 v113, 0, v119
	v_pk_mul_f32 v[98:99], v[98:99], v[98:99]
	v_pk_mul_f32 v[100:101], v[100:101], v[100:101]
	v_pk_mul_f32 v[102:103], v[102:103], v[102:103]
	v_pk_mul_f32 v[104:105], v[104:105], v[104:105]
	v_pk_mul_f32 v[106:107], v[106:107], v[106:107]
	v_pk_mul_f32 v[108:109], v[108:109], v[108:109]
	v_pk_mul_f32 v[110:111], v[110:111], v[110:111]
	v_pk_mul_f32 v[112:113], v[112:113], v[112:113]
	v_max_f32_e32 v60, v60, v60
	v_max_f32_e32 v57, v57, v57
	v_max_f32_e32 v59, v59, v59
	v_max_f32_e32 v45, v45, v45
	v_max_f32_e32 v46, v46, v46
	v_max_f32_e32 v47, v47, v47
	v_max_f32_e32 v40, v40, v40
	v_max_f32_e32 v42, v42, v42
	v_max_f32_e32 v33, v33, v33
	v_max_f32_e32 v44, v44, v44
	v_max_f32_e32 v41, v41, v41
	v_max_f32_e32 v43, v43, v43
	v_max_f32_e32 v29, v29, v29
	v_max_f32_e32 v30, v30, v30
	v_max_f32_e32 v31, v31, v31
	v_max_f32_e32 v24, v24, v24
	v_max_f32_e32 v26, v26, v26
	v_max_f32_e32 v17, v17, v17
	v_max_f32_e32 v28, v28, v28
	v_max_f32_e32 v25, v25, v25
	v_max_f32_e32 v27, v27, v27
	v_max_f32_e32 v15, v15, v15
	v_max_f32_e32 v1, v1, v1
	v_max_f32_e32 v13, v13, v13
	v_max_f32_e32 v14, v14, v14
	v_max_f32_e32 v8, v8, v8
	v_max_f32_e32 v10, v10, v10
	v_max_f32_e32 v12, v12, v12
	v_max_f32_e32 v9, v9, v9
	v_max_f32_e32 v11, v11, v11
	s_waitcnt vmcnt(8)
; __device__ __forceinline__ void st_bf8(bf16* p, f32x4 a, f32x4 b) { u32x4 w; w.x = pk2(a[0], a[1]); w.y = pk2(a[2], a[3]); w.z = pk2(b[0], b[1]); w.w = pk2(b[2], b[3]); *(u32x4*)p = w; }
;     __device__ __forceinline__ void operator()(AccRef acc, const pg8::Unit& u, int wr, int wc, int fr, int fq) const {
;         const int c0 = u.pn * 256;
; #pragma unroll
;         for (int ai = 0; ai < 2; ++ai)
; #pragma unroll
;             for (int m = 0; m < 4; ++m) {
;                 const int row = u.pm * 256 + ai * 128 + wr * 64 + m * 16 + fr; const size_t rw = (size_t)row;
;                 const float rs2 = 1.0f / (SSQ[row] * (1.f / 1024.f) + EPSN);
; #pragma unroll
;                 for (int bj = 0; bj < 2; ++bj) {
;                     const int cl = bj * 128 + wc * 32 + 8 * fq; const f32x4 v0 = acc[ai][bj][m][0], v1 = acc[ai][bj][m][1];
;                     f32x4 r0, r1; r0[0] = fmaxf(v0[0], 0.f); r0[1] = fmaxf(v0[1], 0.f); r0[2] = fmaxf(v0[2], 0.f); r0[3] = fmaxf(v0[3], 0.f); r1[0] = fmaxf(v1[0], 0.f); r1[1] = fmaxf(v1[1], 0.f); r1[2] = fmaxf(v1[2], 0.f); r1[3] = fmaxf(v1[3], 0.f);
;                     st_bf8(U + rw * 4096 + c0 + cl, r0 * r0 * rs2, r1 * r1 * rs2);
;                 }
;                 asm volatile("" ::: "memory");
;             }
;     }
	v_fmamk_f32 v116, v161, 0x3a800000, v205
	v_div_scale_f32 v117, s[28:29], v116, v116, 1.0
	v_rcp_f32_e32 v118, v117
	v_lshl_add_u64 v[114:115], v[96:97], 0, v[184:185]
	v_div_scale_f32 v96, vcc, 1.0, v116, 1.0
	v_fma_f32 v97, -v117, v118, 1.0
	v_fmac_f32_e32 v118, v97, v118
	v_mul_f32_e32 v97, v96, v118
	v_fma_f32 v119, -v117, v97, v96
	v_fmac_f32_e32 v97, v119, v118
	v_fma_f32 v96, -v117, v97, v96
	v_div_fmas_f32 v96, v96, v118, v97
	v_div_fixup_f32 v96, v96, v116, 1.0
	v_pk_mul_f32 v[100:101], v[100:101], v[96:97] op_sel_hi:[1,0]
	v_pk_mul_f32 v[98:99], v[98:99], v[96:97] op_sel_hi:[1,0]
	v_pk_mul_f32 v[104:105], v[104:105], v[96:97] op_sel_hi:[1,0]
	v_pk_mul_f32 v[102:103], v[102:103], v[96:97] op_sel_hi:[1,0]
	v_pk_mul_f32 v[108:109], v[108:109], v[96:97] op_sel_hi:[1,0]
	v_pk_mul_f32 v[106:107], v[106:107], v[96:97] op_sel_hi:[1,0]
	v_pk_mul_f32 v[112:113], v[112:113], v[96:97] op_sel_hi:[1,0]
	v_pk_mul_f32 v[110:111], v[110:111], v[96:97] op_sel_hi:[1,0]
	v_cvt_pk_bf16_f32 v96, v98, v99
	v_cvt_pk_bf16_f32 v97, v100, v101
	v_cvt_pk_bf16_f32 v98, v102, v103
	v_cvt_pk_bf16_f32 v99, v104, v105
	v_cvt_pk_bf16_f32 v100, v106, v107
	v_cvt_pk_bf16_f32 v101, v108, v109
	v_cvt_pk_bf16_f32 v102, v110, v111
	v_cvt_pk_bf16_f32 v103, v112, v113
	global_store_dwordx4 v[114:115], v[96:99], off
	global_store_dwordx4 v[114:115], v[100:103], off offset:256
	s_nop 1
	v_max_f32_e32 v96, v84, v84
	v_max_f32_e32 v100, v87, v87
	v_max_f32_e32 v101, v80, v80
	v_max_f32_e32 v103, v83, v83
	v_max_f32_e32 v83, 0, v93
	v_max_f32_e32 v93, 0, v100
	v_max_f32_e32 v102, v82, v82
	v_or_b32_e32 v80, 32, v140
	v_max_f32_e32 v84, 0, v94
	v_max_f32_e32 v94, 0, v101
	v_max_f32_e32 v97, v85, v85
	v_max_f32_e32 v99, v86, v86
	v_max_f32_e32 v85, 0, v95
	v_max_f32_e32 v86, 0, v88
	v_max_f32_e32 v88, 0, v90
	v_max_f32_e32 v90, 0, v96
	v_max_f32_e32 v95, 0, v81
	v_max_f32_e32 v96, 0, v102
	v_ashrrev_i32_e32 v81, 31, v80
	v_lshlrev_b64 v[80:81], 13, v[80:81]
	v_lshl_add_u64 v[80:81], s[10:11], 0, v[80:81]
	v_lshl_add_u64 v[80:81], v[80:81], 0, s[26:27]
	v_max_f32_e32 v82, 0, v92
	v_max_f32_e32 v92, 0, v99
	v_max_f32_e32 v87, 0, v89
	v_max_f32_e32 v89, 0, v91
	v_max_f32_e32 v91, 0, v97
	v_max_f32_e32 v97, 0, v103
	v_pk_mul_f32 v[82:83], v[82:83], v[82:83]
	v_pk_mul_f32 v[84:85], v[84:85], v[84:85]
	v_pk_mul_f32 v[86:87], v[86:87], v[86:87]
	v_pk_mul_f32 v[88:89], v[88:89], v[88:89]
	v_pk_mul_f32 v[90:91], v[90:91], v[90:91]
	v_pk_mul_f32 v[92:93], v[92:93], v[92:93]
	v_pk_mul_f32 v[94:95], v[94:95], v[94:95]
	v_pk_mul_f32 v[96:97], v[96:97], v[96:97]
	s_waitcnt vmcnt(9)
	v_fmamk_f32 v100, v162, 0x3a800000, v205
	v_div_scale_f32 v101, s[28:29], v100, v100, 1.0
	v_rcp_f32_e32 v102, v101
	v_lshl_add_u64 v[98:99], v[80:81], 0, v[184:185]
	v_div_scale_f32 v80, vcc, 1.0, v100, 1.0
	v_fma_f32 v81, -v101, v102, 1.0
	v_fmac_f32_e32 v102, v81, v102
	v_mul_f32_e32 v81, v80, v102
	v_fma_f32 v103, -v101, v81, v80
	v_fmac_f32_e32 v81, v103, v102
	v_fma_f32 v80, -v101, v81, v80
	v_div_fmas_f32 v80, v80, v102, v81
	v_div_fixup_f32 v80, v80, v100, 1.0
	v_pk_mul_f32 v[84:85], v[84:85], v[80:81] op_sel_hi:[1,0]
	v_pk_mul_f32 v[82:83], v[82:83], v[80:81] op_sel_hi:[1,0]
	v_pk_mul_f32 v[88:89], v[88:89], v[80:81] op_sel_hi:[1,0]
	v_pk_mul_f32 v[86:87], v[86:87], v[80:81] op_sel_hi:[1,0]
	v_pk_mul_f32 v[92:93], v[92:93], v[80:81] op_sel_hi:[1,0]
	v_pk_mul_f32 v[90:91], v[90:91], v[80:81] op_sel_hi:[1,0]
	v_pk_mul_f32 v[96:97], v[96:97], v[80:81] op_sel_hi:[1,0]
	v_pk_mul_f32 v[94:95], v[94:95], v[80:81] op_sel_hi:[1,0]
	v_cvt_pk_bf16_f32 v80, v82, v83
	v_cvt_pk_bf16_f32 v81, v84, v85
	v_cvt_pk_bf16_f32 v82, v86, v87
	v_cvt_pk_bf16_f32 v83, v88, v89
	v_cvt_pk_bf16_f32 v84, v90, v91
	v_cvt_pk_bf16_f32 v85, v92, v93
	v_cvt_pk_bf16_f32 v86, v94, v95
	v_cvt_pk_bf16_f32 v87, v96, v97
	global_store_dwordx4 v[98:99], v[80:83], off
	global_store_dwordx4 v[98:99], v[84:87], off offset:256
	s_nop 1
	v_max_f32_e32 v80, v68, v68
	v_max_f32_e32 v84, v71, v71
	v_max_f32_e32 v85, v64, v64
	v_max_f32_e32 v87, v67, v67
	v_max_f32_e32 v67, 0, v77
	v_max_f32_e32 v77, 0, v84
	v_max_f32_e32 v86, v66, v66
	v_or_b32_e32 v64, 48, v140
	v_max_f32_e32 v68, 0, v78
	v_max_f32_e32 v78, 0, v85
	v_max_f32_e32 v81, v69, v69
	v_max_f32_e32 v83, v70, v70
	v_max_f32_e32 v69, 0, v79
	v_max_f32_e32 v70, 0, v72
	v_max_f32_e32 v72, 0, v74
	v_max_f32_e32 v74, 0, v80
	v_max_f32_e32 v79, 0, v65
	v_max_f32_e32 v80, 0, v86
	v_ashrrev_i32_e32 v65, 31, v64
	v_lshlrev_b64 v[64:65], 13, v[64:65]
	v_lshl_add_u64 v[64:65], s[10:11], 0, v[64:65]
	v_lshl_add_u64 v[64:65], v[64:65], 0, s[26:27]
	v_max_f32_e32 v66, 0, v76
	v_max_f32_e32 v76, 0, v83
	v_max_f32_e32 v71, 0, v73
	v_max_f32_e32 v73, 0, v75
	v_max_f32_e32 v75, 0, v81
	v_max_f32_e32 v81, 0, v87
	v_pk_mul_f32 v[66:67], v[66:67], v[66:67]
	v_pk_mul_f32 v[68:69], v[68:69], v[68:69]
	v_pk_mul_f32 v[70:71], v[70:71], v[70:71]
	v_pk_mul_f32 v[72:73], v[72:73], v[72:73]
	v_pk_mul_f32 v[74:75], v[74:75], v[74:75]
	v_pk_mul_f32 v[76:77], v[76:77], v[76:77]
	v_pk_mul_f32 v[78:79], v[78:79], v[78:79]
	v_pk_mul_f32 v[80:81], v[80:81], v[80:81]
	s_waitcnt vmcnt(10)
; __device__ __forceinline__ void st_bf8(bf16* p, f32x4 a, f32x4 b) { u32x4 w; w.x = pk2(a[0], a[1]); w.y = pk2(a[2], a[3]); w.z = pk2(b[0], b[1]); w.w = pk2(b[2], b[3]); *(u32x4*)p = w; }
;     __device__ __forceinline__ void operator()(AccRef acc, const pg8::Unit& u, int wr, int wc, int fr, int fq) const {
;         const int c0 = u.pn * 256;
; #pragma unroll
;         for (int ai = 0; ai < 2; ++ai)
; #pragma unroll
;             for (int m = 0; m < 4; ++m) {
;                 const int row = u.pm * 256 + ai * 128 + wr * 64 + m * 16 + fr; const size_t rw = (size_t)row;
;                 const float rs2 = 1.0f / (SSQ[row] * (1.f / 1024.f) + EPSN);
; #pragma unroll
;                 for (int bj = 0; bj < 2; ++bj) {
;                     const int cl = bj * 128 + wc * 32 + 8 * fq; const f32x4 v0 = acc[ai][bj][m][0], v1 = acc[ai][bj][m][1];
;                     f32x4 r0, r1; r0[0] = fmaxf(v0[0], 0.f); r0[1] = fmaxf(v0[1], 0.f); r0[2] = fmaxf(v0[2], 0.f); r0[3] = fmaxf(v0[3], 0.f); r1[0] = fmaxf(v1[0], 0.f); r1[1] = fmaxf(v1[1], 0.f); r1[2] = fmaxf(v1[2], 0.f); r1[3] = fmaxf(v1[3], 0.f);
;                     st_bf8(U + rw * 4096 + c0 + cl, r0 * r0 * rs2, r1 * r1 * rs2);
;                 }
;                 asm volatile("" ::: "memory");
;             }
;     }
	v_fmamk_f32 v84, v163, 0x3a800000, v205
	v_div_scale_f32 v85, s[28:29], v84, v84, 1.0
	v_rcp_f32_e32 v86, v85
	v_lshl_add_u64 v[82:83], v[64:65], 0, v[184:185]
	v_div_scale_f32 v64, vcc, 1.0, v84, 1.0
	v_fma_f32 v65, -v85, v86, 1.0
	v_fmac_f32_e32 v86, v65, v86
	v_mul_f32_e32 v65, v64, v86
	v_fma_f32 v87, -v85, v65, v64
	v_fmac_f32_e32 v65, v87, v86
	v_fma_f32 v64, -v85, v65, v64
	v_div_fmas_f32 v64, v64, v86, v65
	v_div_fixup_f32 v64, v64, v84, 1.0
	v_pk_mul_f32 v[68:69], v[68:69], v[64:65] op_sel_hi:[1,0]
	v_pk_mul_f32 v[66:67], v[66:67], v[64:65] op_sel_hi:[1,0]
	v_pk_mul_f32 v[72:73], v[72:73], v[64:65] op_sel_hi:[1,0]
	v_pk_mul_f32 v[70:71], v[70:71], v[64:65] op_sel_hi:[1,0]
	v_pk_mul_f32 v[76:77], v[76:77], v[64:65] op_sel_hi:[1,0]
	v_pk_mul_f32 v[74:75], v[74:75], v[64:65] op_sel_hi:[1,0]
	v_pk_mul_f32 v[80:81], v[80:81], v[64:65] op_sel_hi:[1,0]
	v_pk_mul_f32 v[78:79], v[78:79], v[64:65] op_sel_hi:[1,0]
	v_cvt_pk_bf16_f32 v64, v66, v67
	v_cvt_pk_bf16_f32 v65, v68, v69
	v_cvt_pk_bf16_f32 v66, v70, v71
	v_cvt_pk_bf16_f32 v67, v72, v73
	v_cvt_pk_bf16_f32 v68, v74, v75
	v_cvt_pk_bf16_f32 v69, v76, v77
	v_cvt_pk_bf16_f32 v70, v78, v79
	v_cvt_pk_bf16_f32 v71, v80, v81
	global_store_dwordx4 v[82:83], v[64:67], off
	global_store_dwordx4 v[82:83], v[68:71], off offset:256
	s_nop 1
	v_max_f32_e32 v64, v52, v52
	v_max_f32_e32 v68, v55, v55
	v_max_f32_e32 v69, v48, v48
	v_max_f32_e32 v71, v51, v51
	v_max_f32_e32 v51, 0, v61
	v_max_f32_e32 v61, 0, v68
	v_max_f32_e32 v70, v50, v50
	v_add_u32_e32 v48, 0x80, v140
	v_max_f32_e32 v52, 0, v62
	v_max_f32_e32 v62, 0, v69
	v_max_f32_e32 v65, v53, v53
	v_max_f32_e32 v67, v54, v54
	v_max_f32_e32 v53, 0, v63
	v_max_f32_e32 v54, 0, v56
	v_max_f32_e32 v56, 0, v58
	v_max_f32_e32 v58, 0, v64
	v_max_f32_e32 v63, 0, v49
	v_max_f32_e32 v64, 0, v70
	v_ashrrev_i32_e32 v49, 31, v48
	v_lshlrev_b64 v[48:49], 13, v[48:49]
	v_lshl_add_u64 v[48:49], s[10:11], 0, v[48:49]
	v_lshl_add_u64 v[48:49], v[48:49], 0, s[26:27]
	v_max_f32_e32 v50, 0, v60
	v_max_f32_e32 v60, 0, v67
	v_max_f32_e32 v55, 0, v57
	v_max_f32_e32 v57, 0, v59
	v_max_f32_e32 v59, 0, v65
	v_max_f32_e32 v65, 0, v71
	v_pk_mul_f32 v[50:51], v[50:51], v[50:51]
	v_pk_mul_f32 v[52:53], v[52:53], v[52:53]
	v_pk_mul_f32 v[54:55], v[54:55], v[54:55]
	v_pk_mul_f32 v[56:57], v[56:57], v[56:57]
	v_pk_mul_f32 v[58:59], v[58:59], v[58:59]
	v_pk_mul_f32 v[60:61], v[60:61], v[60:61]
	v_pk_mul_f32 v[62:63], v[62:63], v[62:63]
	v_pk_mul_f32 v[64:65], v[64:65], v[64:65]
	s_waitcnt vmcnt(11)
	v_fmamk_f32 v68, v164, 0x3a800000, v205
	v_div_scale_f32 v69, s[28:29], v68, v68, 1.0
	v_rcp_f32_e32 v70, v69
	v_lshl_add_u64 v[66:67], v[48:49], 0, v[184:185]
	v_div_scale_f32 v48, vcc, 1.0, v68, 1.0
	v_fma_f32 v49, -v69, v70, 1.0
	v_fmac_f32_e32 v70, v49, v70
	v_mul_f32_e32 v49, v48, v70
	v_fma_f32 v71, -v69, v49, v48
	v_fmac_f32_e32 v49, v71, v70
	v_fma_f32 v48, -v69, v49, v48
	v_div_fmas_f32 v48, v48, v70, v49
	v_div_fixup_f32 v48, v48, v68, 1.0
	v_pk_mul_f32 v[52:53], v[52:53], v[48:49] op_sel_hi:[1,0]
	v_pk_mul_f32 v[50:51], v[50:51], v[48:49] op_sel_hi:[1,0]
	v_pk_mul_f32 v[56:57], v[56:57], v[48:49] op_sel_hi:[1,0]
	v_pk_mul_f32 v[54:55], v[54:55], v[48:49] op_sel_hi:[1,0]
	v_pk_mul_f32 v[60:61], v[60:61], v[48:49] op_sel_hi:[1,0]
	v_pk_mul_f32 v[58:59], v[58:59], v[48:49] op_sel_hi:[1,0]
	v_pk_mul_f32 v[64:65], v[64:65], v[48:49] op_sel_hi:[1,0]
	v_pk_mul_f32 v[62:63], v[62:63], v[48:49] op_sel_hi:[1,0]
	v_cvt_pk_bf16_f32 v48, v50, v51
	v_cvt_pk_bf16_f32 v49, v52, v53
	v_cvt_pk_bf16_f32 v50, v54, v55
	v_cvt_pk_bf16_f32 v51, v56, v57
	v_cvt_pk_bf16_f32 v52, v58, v59
	v_cvt_pk_bf16_f32 v53, v60, v61
	v_cvt_pk_bf16_f32 v54, v62, v63
	v_cvt_pk_bf16_f32 v55, v64, v65
	global_store_dwordx4 v[66:67], v[48:51], off
	global_store_dwordx4 v[66:67], v[52:55], off offset:256
	s_nop 1
	v_max_f32_e32 v48, v36, v36
	v_max_f32_e32 v52, v39, v39
	v_max_f32_e32 v53, v32, v32
	v_max_f32_e32 v55, v35, v35
	v_max_f32_e32 v35, 0, v45
	v_max_f32_e32 v45, 0, v52
	v_max_f32_e32 v54, v34, v34
	v_add_u32_e32 v32, 0x90, v140
	v_max_f32_e32 v36, 0, v46
	v_max_f32_e32 v46, 0, v53
	v_max_f32_e32 v49, v37, v37
	v_max_f32_e32 v51, v38, v38
	v_max_f32_e32 v37, 0, v47
	v_max_f32_e32 v38, 0, v40
	v_max_f32_e32 v40, 0, v42
	v_max_f32_e32 v42, 0, v48
	v_max_f32_e32 v47, 0, v33
	v_max_f32_e32 v48, 0, v54
	v_ashrrev_i32_e32 v33, 31, v32
	v_lshlrev_b64 v[32:33], 13, v[32:33]
	v_lshl_add_u64 v[32:33], s[10:11], 0, v[32:33]
	v_lshl_add_u64 v[32:33], v[32:33], 0, s[26:27]
	v_max_f32_e32 v34, 0, v44
	v_max_f32_e32 v44, 0, v51
	v_max_f32_e32 v39, 0, v41
	v_max_f32_e32 v41, 0, v43
	v_max_f32_e32 v43, 0, v49
	v_max_f32_e32 v49, 0, v55
	v_pk_mul_f32 v[34:35], v[34:35], v[34:35]
	v_pk_mul_f32 v[36:37], v[36:37], v[36:37]
	v_pk_mul_f32 v[38:39], v[38:39], v[38:39]
	v_pk_mul_f32 v[40:41], v[40:41], v[40:41]
	v_pk_mul_f32 v[42:43], v[42:43], v[42:43]
	v_pk_mul_f32 v[44:45], v[44:45], v[44:45]
	v_pk_mul_f32 v[46:47], v[46:47], v[46:47]
	v_pk_mul_f32 v[48:49], v[48:49], v[48:49]
	s_waitcnt vmcnt(12)
; __device__ __forceinline__ void st_bf8(bf16* p, f32x4 a, f32x4 b) { u32x4 w; w.x = pk2(a[0], a[1]); w.y = pk2(a[2], a[3]); w.z = pk2(b[0], b[1]); w.w = pk2(b[2], b[3]); *(u32x4*)p = w; }
;     __device__ __forceinline__ void operator()(AccRef acc, const pg8::Unit& u, int wr, int wc, int fr, int fq) const {
;         const int c0 = u.pn * 256;
; #pragma unroll
;         for (int ai = 0; ai < 2; ++ai)
; #pragma unroll
;             for (int m = 0; m < 4; ++m) {
;                 const int row = u.pm * 256 + ai * 128 + wr * 64 + m * 16 + fr; const size_t rw = (size_t)row;
;                 const float rs2 = 1.0f / (SSQ[row] * (1.f / 1024.f) + EPSN);
; #pragma unroll
;                 for (int bj = 0; bj < 2; ++bj) {
;                     const int cl = bj * 128 + wc * 32 + 8 * fq; const f32x4 v0 = acc[ai][bj][m][0], v1 = acc[ai][bj][m][1];
;                     f32x4 r0, r1; r0[0] = fmaxf(v0[0], 0.f); r0[1] = fmaxf(v0[1], 0.f); r0[2] = fmaxf(v0[2], 0.f); r0[3] = fmaxf(v0[3], 0.f); r1[0] = fmaxf(v1[0], 0.f); r1[1] = fmaxf(v1[1], 0.f); r1[2] = fmaxf(v1[2], 0.f); r1[3] = fmaxf(v1[3], 0.f);
;                     st_bf8(U + rw * 4096 + c0 + cl, r0 * r0 * rs2, r1 * r1 * rs2);
;                 }
;                 asm volatile("" ::: "memory");
;             }
;     }
	v_fmamk_f32 v52, v165, 0x3a800000, v205
	v_div_scale_f32 v53, s[28:29], v52, v52, 1.0
	v_rcp_f32_e32 v54, v53
	v_lshl_add_u64 v[50:51], v[32:33], 0, v[184:185]
	v_div_scale_f32 v32, vcc, 1.0, v52, 1.0
	v_fma_f32 v33, -v53, v54, 1.0
	v_fmac_f32_e32 v54, v33, v54
	v_mul_f32_e32 v33, v32, v54
	v_fma_f32 v55, -v53, v33, v32
	v_fmac_f32_e32 v33, v55, v54
	v_fma_f32 v32, -v53, v33, v32
	v_div_fmas_f32 v32, v32, v54, v33
	v_div_fixup_f32 v32, v32, v52, 1.0
	v_pk_mul_f32 v[36:37], v[36:37], v[32:33] op_sel_hi:[1,0]
	v_pk_mul_f32 v[34:35], v[34:35], v[32:33] op_sel_hi:[1,0]
	v_pk_mul_f32 v[40:41], v[40:41], v[32:33] op_sel_hi:[1,0]
	v_pk_mul_f32 v[38:39], v[38:39], v[32:33] op_sel_hi:[1,0]
	v_pk_mul_f32 v[44:45], v[44:45], v[32:33] op_sel_hi:[1,0]
	v_pk_mul_f32 v[42:43], v[42:43], v[32:33] op_sel_hi:[1,0]
	v_pk_mul_f32 v[48:49], v[48:49], v[32:33] op_sel_hi:[1,0]
	v_pk_mul_f32 v[46:47], v[46:47], v[32:33] op_sel_hi:[1,0]
	v_cvt_pk_bf16_f32 v32, v34, v35
	v_cvt_pk_bf16_f32 v33, v36, v37
	v_cvt_pk_bf16_f32 v34, v38, v39
	v_cvt_pk_bf16_f32 v35, v40, v41
	v_cvt_pk_bf16_f32 v36, v42, v43
	v_cvt_pk_bf16_f32 v37, v44, v45
	v_cvt_pk_bf16_f32 v38, v46, v47
	v_cvt_pk_bf16_f32 v39, v48, v49
	global_store_dwordx4 v[50:51], v[32:35], off
	global_store_dwordx4 v[50:51], v[36:39], off offset:256
	s_nop 1
	v_max_f32_e32 v32, v20, v20
	v_max_f32_e32 v36, v23, v23
	v_max_f32_e32 v37, v16, v16
	v_max_f32_e32 v39, v19, v19
	v_max_f32_e32 v19, 0, v29
	v_max_f32_e32 v29, 0, v36
	v_max_f32_e32 v38, v18, v18
	v_add_u32_e32 v16, 0xa0, v140
	v_max_f32_e32 v20, 0, v30
	v_max_f32_e32 v30, 0, v37
	v_max_f32_e32 v33, v21, v21
	v_max_f32_e32 v35, v22, v22
	v_max_f32_e32 v21, 0, v31
	v_max_f32_e32 v22, 0, v24
	v_max_f32_e32 v24, 0, v26
	v_max_f32_e32 v26, 0, v32
	v_max_f32_e32 v31, 0, v17
	v_max_f32_e32 v32, 0, v38
	v_ashrrev_i32_e32 v17, 31, v16
	v_lshlrev_b64 v[16:17], 13, v[16:17]
	v_lshl_add_u64 v[16:17], s[10:11], 0, v[16:17]
	v_lshl_add_u64 v[16:17], v[16:17], 0, s[26:27]
	v_max_f32_e32 v18, 0, v28
	v_max_f32_e32 v28, 0, v35
	v_max_f32_e32 v23, 0, v25
	v_max_f32_e32 v25, 0, v27
	v_max_f32_e32 v27, 0, v33
	v_max_f32_e32 v33, 0, v39
	v_pk_mul_f32 v[18:19], v[18:19], v[18:19]
	v_pk_mul_f32 v[20:21], v[20:21], v[20:21]
	v_pk_mul_f32 v[22:23], v[22:23], v[22:23]
	v_pk_mul_f32 v[24:25], v[24:25], v[24:25]
	v_pk_mul_f32 v[26:27], v[26:27], v[26:27]
	v_pk_mul_f32 v[28:29], v[28:29], v[28:29]
	v_pk_mul_f32 v[30:31], v[30:31], v[30:31]
	v_pk_mul_f32 v[32:33], v[32:33], v[32:33]
	s_waitcnt vmcnt(13)
	v_fmamk_f32 v36, v166, 0x3a800000, v205
	v_div_scale_f32 v37, s[28:29], v36, v36, 1.0
	v_rcp_f32_e32 v38, v37
	v_lshl_add_u64 v[34:35], v[16:17], 0, v[184:185]
	v_div_scale_f32 v16, vcc, 1.0, v36, 1.0
	v_fma_f32 v17, -v37, v38, 1.0
	v_fmac_f32_e32 v38, v17, v38
	v_mul_f32_e32 v17, v16, v38
	v_fma_f32 v39, -v37, v17, v16
	v_fmac_f32_e32 v17, v39, v38
	v_fma_f32 v16, -v37, v17, v16
	v_div_fmas_f32 v16, v16, v38, v17
	v_div_fixup_f32 v16, v16, v36, 1.0
	v_pk_mul_f32 v[20:21], v[20:21], v[16:17] op_sel_hi:[1,0]
	v_pk_mul_f32 v[18:19], v[18:19], v[16:17] op_sel_hi:[1,0]
	v_pk_mul_f32 v[24:25], v[24:25], v[16:17] op_sel_hi:[1,0]
	v_pk_mul_f32 v[22:23], v[22:23], v[16:17] op_sel_hi:[1,0]
	v_pk_mul_f32 v[28:29], v[28:29], v[16:17] op_sel_hi:[1,0]
	v_pk_mul_f32 v[26:27], v[26:27], v[16:17] op_sel_hi:[1,0]
	v_pk_mul_f32 v[32:33], v[32:33], v[16:17] op_sel_hi:[1,0]
	v_pk_mul_f32 v[30:31], v[30:31], v[16:17] op_sel_hi:[1,0]
	v_cvt_pk_bf16_f32 v16, v18, v19
	v_cvt_pk_bf16_f32 v17, v20, v21
	v_cvt_pk_bf16_f32 v18, v22, v23
	v_cvt_pk_bf16_f32 v19, v24, v25
	v_cvt_pk_bf16_f32 v20, v26, v27
	v_cvt_pk_bf16_f32 v21, v28, v29
	v_cvt_pk_bf16_f32 v22, v30, v31
	v_cvt_pk_bf16_f32 v23, v32, v33
	global_store_dwordx4 v[34:35], v[16:19], off
	global_store_dwordx4 v[34:35], v[20:23], off offset:256
	s_nop 1
	v_max_f32_e32 v17, v5, v5
	v_max_f32_e32 v21, v0, v0
	v_add_u32_e32 v0, 0xb0, v140
	v_max_f32_e32 v5, 0, v15
	v_max_f32_e32 v15, 0, v1
	v_ashrrev_i32_e32 v1, 31, v0
	v_max_f32_e32 v20, v7, v7
	v_lshlrev_b64 v[0:1], 13, v[0:1]
	v_max_f32_e32 v23, v3, v3
	v_max_f32_e32 v3, 0, v13
	v_max_f32_e32 v13, 0, v20
	v_lshl_add_u64 v[0:1], s[10:11], 0, v[0:1]
	v_max_f32_e32 v16, v4, v4
	v_max_f32_e32 v22, v2, v2
	v_max_f32_e32 v4, 0, v14
	v_max_f32_e32 v14, 0, v21
	v_lshl_add_u64 v[0:1], v[0:1], 0, s[26:27]
	v_max_f32_e32 v19, v6, v6
	v_max_f32_e32 v6, 0, v8
	v_max_f32_e32 v8, 0, v10
	v_max_f32_e32 v10, 0, v16
	v_max_f32_e32 v16, 0, v22
	v_max_f32_e32 v2, 0, v12
	v_max_f32_e32 v12, 0, v19
	v_max_f32_e32 v7, 0, v9
	v_max_f32_e32 v9, 0, v11
	v_max_f32_e32 v11, 0, v17
	v_max_f32_e32 v17, 0, v23
	v_pk_mul_f32 v[2:3], v[2:3], v[2:3]
	v_pk_mul_f32 v[4:5], v[4:5], v[4:5]
	v_pk_mul_f32 v[6:7], v[6:7], v[6:7]
	v_pk_mul_f32 v[8:9], v[8:9], v[8:9]
	v_pk_mul_f32 v[10:11], v[10:11], v[10:11]
	v_pk_mul_f32 v[12:13], v[12:13], v[12:13]
	v_pk_mul_f32 v[14:15], v[14:15], v[14:15]
	v_pk_mul_f32 v[16:17], v[16:17], v[16:17]
	s_waitcnt vmcnt(14)
	v_fmamk_f32 v20, v167, 0x3a800000, v205
	v_div_scale_f32 v21, s[26:27], v20, v20, 1.0
	v_rcp_f32_e32 v22, v21
	v_lshl_add_u64 v[18:19], v[0:1], 0, v[184:185]
	v_div_scale_f32 v0, vcc, 1.0, v20, 1.0
	v_fma_f32 v1, -v21, v22, 1.0
	v_fmac_f32_e32 v22, v1, v22
	v_mul_f32_e32 v1, v0, v22
	v_fma_f32 v23, -v21, v1, v0
	v_fmac_f32_e32 v1, v23, v22
	v_fma_f32 v0, -v21, v1, v0
	v_div_fmas_f32 v0, v0, v22, v1
	v_div_fixup_f32 v0, v0, v20, 1.0
	v_pk_mul_f32 v[4:5], v[4:5], v[0:1] op_sel_hi:[1,0]
	v_pk_mul_f32 v[2:3], v[2:3], v[0:1] op_sel_hi:[1,0]
	v_pk_mul_f32 v[8:9], v[8:9], v[0:1] op_sel_hi:[1,0]
	v_pk_mul_f32 v[6:7], v[6:7], v[0:1] op_sel_hi:[1,0]
	v_pk_mul_f32 v[12:13], v[12:13], v[0:1] op_sel_hi:[1,0]
	v_pk_mul_f32 v[10:11], v[10:11], v[0:1] op_sel_hi:[1,0]
	v_pk_mul_f32 v[16:17], v[16:17], v[0:1] op_sel_hi:[1,0]
	v_pk_mul_f32 v[14:15], v[14:15], v[0:1] op_sel_hi:[1,0]
	v_cvt_pk_bf16_f32 v0, v2, v3
	v_cvt_pk_bf16_f32 v1, v4, v5
	v_cvt_pk_bf16_f32 v2, v6, v7
	v_cvt_pk_bf16_f32 v3, v8, v9
	v_cvt_pk_bf16_f32 v4, v10, v11
	v_cvt_pk_bf16_f32 v5, v12, v13
	v_cvt_pk_bf16_f32 v6, v14, v15
	v_cvt_pk_bf16_f32 v7, v16, v17
	global_store_dwordx4 v[18:19], v[0:3], off
	global_store_dwordx4 v[18:19], v[4:7], off offset:256
	s_and_b64 vcc, exec, s[0:1]
	s_mov_b64 s[0:1], -1
	s_cbranch_vccnz .LBB0_320
	s_andn2_b64 vcc, exec, s[16:17]
	s_cbranch_vccnz .LBB0_319
	s_barrier
	s_branch .LBB0_319
